# PIN1: code placement test: one 4-byte s_nop before the layer loop (all per-layer loops shifted by 4 bytes, 8-byte phase flipped)
# speedup vs baseline: 1.0032x; 1.0013x over previous
; __global__ void __launch_bounds__(NTHREADS, 2) hymba_fwd(Args a) {
;     ...
;     for (int layer = 0; layer < 2; ++layer) {
;         const int pb = 2 + 3 * layer;
;         if (IN(pb)) {
.LBB0_163:
	s_mov_b64 s[0:1], 0
	v_writelane_b32 v254, s0, 53
	s_mov_b32 s99, 1
	s_nop 0
	v_writelane_b32 v254, s1, 54
	v_readlane_b32 s0, v255, 8
	v_readlane_b32 s1, v255, 9
	s_and_b64 vcc, exec, s[0:1]
	s_cbranch_vccnz .LBB0_552
	s_nop 0
